# attention steady loop: no s_nop left between MFMAs (m0 wait state filled with a pack, lane-swap copy made one gap earlier, row-sum accumulate between compare and scalar copy)
# speedup vs baseline: 1.0053x; 1.0026x over previous
.Latt_head:
	s_lshl_b32 s14, s14, 1
	v_add_u32_e32 v217, s14, v244
	ds_read_b64_tr_b16 v[208:209], v217 offset:24576
	ds_read_b64_tr_b16 v[210:211], v217 offset:25088
	v_add_f32_e32 v112, v96, v97
	v_add_f32_e32 v112, v98, v112
	v_add_f32_e32 v112, v99, v112
	v_add_f32_e32 v112, v100, v112
	v_add_f32_e32 v112, v101, v112
	v_cvt_pk_bf16_f32 v164, v96, v97
	v_cvt_pk_bf16_f32 v165, v98, v99
	ds_read_b64_tr_b16 v[96:97], v217 offset:28672
	ds_read_b64_tr_b16 v[98:99], v217 offset:29184
	v_add_f32_e32 v112, v102, v112
	v_add_f32_e32 v112, v103, v112
	v_add_f32_e32 v112, v104, v112
	v_add_f32_e32 v144, v105, v112
	v_mfma_f32_32x32x16_bf16 v[112:127], v[200:203], v[172:175], v[64:79]
	v_cvt_pk_bf16_f32 v166, v100, v101
	v_cvt_pk_bf16_f32 v167, v102, v103
	ds_read_b64_tr_b16 v[100:101], v217 offset:25600
	ds_read_b64_tr_b16 v[102:103], v217 offset:26112
	v_mfma_f32_32x32x16_bf16 v[128:143], v[196:199], v[168:171], v[128:143]
	v_add_f32_e32 v144, v106, v144
	v_add_f32_e32 v144, v107, v144
	v_add_f32_e32 v144, v108, v144
	v_add_f32_e32 v144, v109, v144
	v_cvt_pk_bf16_f32 v156, v104, v105
	v_cvt_pk_bf16_f32 v157, v106, v107
	ds_read_b64_tr_b16 v[104:105], v217 offset:29696
	ds_read_b64_tr_b16 v[106:107], v217 offset:30208
	v_mfma_f32_32x32x16_bf16 v[112:127], v[192:195], v[168:171], v[112:127]
	v_add_f32_e32 v144, v110, v144
	v_add_f32_e32 v144, v111, v144
	v_add_f32_e32 v144, v80, v144
	v_add_f32_e32 v144, v81, v144
	v_cvt_pk_bf16_f32 v158, v108, v109
	v_cvt_pk_bf16_f32 v159, v110, v111
	ds_read_b64_tr_b16 v[108:109], v217 offset:26624
	ds_read_b64_tr_b16 v[110:111], v217 offset:27136
	v_mfma_f32_32x32x16_bf16 v[128:143], v[188:191], v[160:163], v[128:143]
	v_add_f32_e32 v144, v82, v144
	v_add_f32_e32 v144, v83, v144
	v_add_f32_e32 v144, v84, v144
	v_add_f32_e32 v144, v85, v144
	v_cvt_pk_bf16_f32 v148, v80, v81
	v_cvt_pk_bf16_f32 v149, v82, v83
	ds_read_b64_tr_b16 v[80:81], v217 offset:30720
	ds_read_b64_tr_b16 v[82:83], v217 offset:31232
	v_mfma_f32_32x32x16_bf16 v[112:127], v[184:187], v[160:163], v[112:127]
	v_add_f32_e32 v144, v86, v144
	v_add_f32_e32 v144, v87, v144
	v_add_f32_e32 v144, v88, v144
	v_add_f32_e32 v144, v89, v144
	v_cvt_pk_bf16_f32 v150, v84, v85
	v_cvt_pk_bf16_f32 v151, v86, v87
	ds_read_b64_tr_b16 v[84:85], v217 offset:27648
	ds_read_b64_tr_b16 v[86:87], v217 offset:28160
	v_mfma_f32_32x32x16_bf16 v[128:143], v[180:183], v[152:155], v[128:143]
	v_add_f32_e32 v144, v90, v144
	v_add_f32_e32 v144, v91, v144
	v_add_f32_e32 v144, v92, v144
	v_add_f32_e32 v180, v93, v144
	v_cvt_pk_bf16_f32 v144, v88, v89
	v_cvt_pk_bf16_f32 v145, v90, v91
	ds_read_b64_tr_b16 v[88:89], v217 offset:31744
	ds_read_b64_tr_b16 v[90:91], v217 offset:32256
	v_mfma_f32_32x32x16_bf16 v[112:127], v[176:179], v[152:155], v[112:127]
	v_add_f32_e32 v146, v94, v180
	v_add_f32_e32 v176, v95, v146
	v_cvt_pk_bf16_f32 v146, v92, v93
	s_add_i32 m0, s24, s63
	s_mov_b32 s14, s32
	s_mov_b32 s15, s70
	global_load_lds_dwordx4 v212, s[14:15]
	s_lshl_b32 s14, s22, 1
	s_add_i32 s14, s14, s64
	s_mov_b32 m0, s14
	s_add_i32 s14, s14, 0x1f80
	global_load_lds_dwordx4 v226, s[98:99]
	s_mov_b32 m0, s14
	v_cvt_pk_bf16_f32 v147, v94, v95
	global_load_lds_dwordx4 v226, s[98:99] offset:128
	s_waitcnt lgkmcnt(12)
	v_mfma_f32_32x32x16_bf16 v[32:47], v[164:167], v[208:211], v[32:47]
	v_max_f32_e32 v222, v128, v129
	v_max3_f32 v223, v130, v131, v113
	v_max3_f32 v222, v222, v112, v114
	v_max3_f32 v222, v222, v115, v132
	ds_read_b64_tr_b16 v[92:93], v217 offset:32768
	ds_read_b64_tr_b16 v[94:95], v217 offset:33280
	v_mfma_f32_32x32x16_bf16 v[48:63], v[164:167], v[96:99], v[48:63]
	v_max3_f32 v223, v223, v134, v135
	v_max3_f32 v222, v222, v133, v116
	v_max3_f32 v223, v223, v118, v119
	v_max3_f32 v222, v222, v117, v136
	ds_read_b64_tr_b16 v[96:97], v217 offset:36864
	ds_read_b64_tr_b16 v[98:99], v217 offset:37376
	s_waitcnt lgkmcnt(12)
	v_mfma_f32_32x32x16_bf16 v[32:47], v[156:159], v[100:103], v[32:47]
	v_max3_f32 v223, v223, v138, v139
	v_max3_f32 v222, v222, v137, v120
	v_max3_f32 v223, v223, v122, v123
	v_max3_f32 v222, v222, v121, v140
	ds_read_b64_tr_b16 v[100:101], v217 offset:33792
	ds_read_b64_tr_b16 v[102:103], v217 offset:34304
	v_mfma_f32_32x32x16_bf16 v[48:63], v[156:159], v[104:107], v[48:63]
	v_max3_f32 v223, v223, v142, v143
	v_max3_f32 v222, v222, v141, v124
	v_max3_f32 v223, v223, v126, v127
	v_max3_f32 v222, v222, v125, v223
	v_mov_b32_e32 v223, v222
	ds_read_b64_tr_b16 v[104:105], v217 offset:37888
	ds_read_b64_tr_b16 v[106:107], v217 offset:38400
	s_waitcnt lgkmcnt(12)
	v_mfma_f32_32x32x16_bf16 v[32:47], v[148:151], v[108:111], v[32:47]
	v_permlane32_swap_b32_e32 v222, v223
	v_max_f32_e32 v222, v222, v223
	v_cmp_lt_f32_e32 vcc, s33, v222
	v_add_f32_e32 v215, v249, v176
	s_mov_b64 s[20:21], vcc
	s_cbranch_vccnz .LBB0_318

.LBB0_313:
	v_mfma_f32_32x32x16_bf16 v[96:111], v[80:83], v[172:175], v[64:79]
	s_add_i32 s14, s22, 0x2000
	s_cmpk_lg_i32 s22, 0x4000
	s_cselect_b32 s66, s14, 0
	s_lshl_b32 s14, s24, 1
	v_add_u32_e32 v209, s14, v244
	ds_read_b64_tr_b16 v[188:189], v209 offset:24576
	ds_read_b64_tr_b16 v[190:191], v209 offset:25088
	v_add_f32_e32 v84, v128, v129
	v_add_f32_e32 v84, v130, v84
	v_add_f32_e32 v84, v131, v84
	v_add_f32_e32 v84, v132, v84
	v_add_f32_e32 v84, v133, v84
	v_cvt_pk_bf16_f32 v164, v128, v129
	v_cvt_pk_bf16_f32 v165, v130, v131
	ds_read_b64_tr_b16 v[128:129], v209 offset:28672
	ds_read_b64_tr_b16 v[130:131], v209 offset:29184
	v_add_f32_e32 v80, v134, v84
	v_add_f32_e32 v80, v135, v80
	v_add_f32_e32 v80, v136, v80
	v_add_f32_e32 v144, v137, v80
	v_mfma_f32_32x32x16_bf16 v[80:95], v[200:203], v[172:175], v[64:79]
	v_cvt_pk_bf16_f32 v166, v132, v133
	v_cvt_pk_bf16_f32 v167, v134, v135
	ds_read_b64_tr_b16 v[132:133], v209 offset:25600
	ds_read_b64_tr_b16 v[134:135], v209 offset:26112
	v_mfma_f32_32x32x16_bf16 v[96:111], v[204:207], v[168:171], v[96:111]
	v_add_f32_e32 v144, v138, v144
	v_add_f32_e32 v144, v139, v144
	v_add_f32_e32 v144, v140, v144
	v_add_f32_e32 v144, v141, v144
	v_cvt_pk_bf16_f32 v156, v136, v137
	v_cvt_pk_bf16_f32 v157, v138, v139
	ds_read_b64_tr_b16 v[136:137], v209 offset:29696
	ds_read_b64_tr_b16 v[138:139], v209 offset:30208
	v_mfma_f32_32x32x16_bf16 v[80:95], v[196:199], v[168:171], v[80:95]
	v_add_f32_e32 v144, v142, v144
	v_add_f32_e32 v144, v143, v144
	v_add_f32_e32 v144, v112, v144
	v_add_f32_e32 v144, v113, v144
	v_cvt_pk_bf16_f32 v158, v140, v141
	v_cvt_pk_bf16_f32 v159, v142, v143
	ds_read_b64_tr_b16 v[140:141], v209 offset:26624
	ds_read_b64_tr_b16 v[142:143], v209 offset:27136
	v_mfma_f32_32x32x16_bf16 v[96:111], v[192:195], v[160:163], v[96:111]
	v_add_f32_e32 v144, v114, v144
	v_add_f32_e32 v144, v115, v144
	v_add_f32_e32 v144, v116, v144
	v_add_f32_e32 v144, v117, v144
	v_cvt_pk_bf16_f32 v148, v112, v113
	v_cvt_pk_bf16_f32 v149, v114, v115
	ds_read_b64_tr_b16 v[112:113], v209 offset:30720
	ds_read_b64_tr_b16 v[114:115], v209 offset:31232
	v_mfma_f32_32x32x16_bf16 v[80:95], v[184:187], v[160:163], v[80:95]
	v_add_f32_e32 v144, v118, v144
	v_add_f32_e32 v144, v119, v144
	v_add_f32_e32 v144, v120, v144
	v_add_f32_e32 v144, v121, v144
	v_cvt_pk_bf16_f32 v150, v116, v117
	v_cvt_pk_bf16_f32 v151, v118, v119
	ds_read_b64_tr_b16 v[116:117], v209 offset:27648
	ds_read_b64_tr_b16 v[118:119], v209 offset:28160
	v_mfma_f32_32x32x16_bf16 v[96:111], v[180:183], v[152:155], v[96:111]
	v_add_f32_e32 v144, v122, v144
	v_add_f32_e32 v144, v123, v144
	v_add_f32_e32 v144, v124, v144
	v_add_f32_e32 v180, v125, v144
	v_cvt_pk_bf16_f32 v144, v120, v121
	v_cvt_pk_bf16_f32 v145, v122, v123
	ds_read_b64_tr_b16 v[120:121], v209 offset:31744
	ds_read_b64_tr_b16 v[122:123], v209 offset:32256
	v_mfma_f32_32x32x16_bf16 v[80:95], v[176:179], v[152:155], v[80:95]
	v_add_f32_e32 v146, v126, v180
	v_add_f32_e32 v176, v127, v146
	v_cvt_pk_bf16_f32 v146, v124, v125
	s_add_i32 m0, s22, s63
	s_add_u32 s14, s32, 0x20000
	s_addc_u32 s15, s70, 0
	global_load_lds_dwordx4 v212, s[14:15]
	s_lshl_b32 s20, s66, 1
	s_add_i32 s20, s20, s64
	s_add_u32 s14, s98, 0x20000
	s_addc_u32 s15, s99, 0
	s_mov_b32 m0, s20
	s_add_i32 s20, s20, 0x1f80
	global_load_lds_dwordx4 v226, s[14:15]
	s_mov_b32 m0, s20
	v_cvt_pk_bf16_f32 v147, v126, v127
	global_load_lds_dwordx4 v226, s[14:15] offset:128
	s_waitcnt lgkmcnt(12)
	v_mfma_f32_32x32x16_bf16 v[32:47], v[164:167], v[188:191], v[32:47]
	v_max_f32_e32 v224, v96, v97
	v_max3_f32 v225, v98, v99, v81
	v_max3_f32 v224, v224, v80, v82
	v_max3_f32 v224, v224, v83, v100
	ds_read_b64_tr_b16 v[124:125], v209 offset:32768
	ds_read_b64_tr_b16 v[126:127], v209 offset:33280
	v_mfma_f32_32x32x16_bf16 v[48:63], v[164:167], v[128:131], v[48:63]
	v_max3_f32 v225, v225, v102, v103
	v_max3_f32 v224, v224, v101, v84
	v_max3_f32 v225, v225, v86, v87
	v_max3_f32 v224, v224, v85, v104
	ds_read_b64_tr_b16 v[128:129], v209 offset:36864
	ds_read_b64_tr_b16 v[130:131], v209 offset:37376
	s_waitcnt lgkmcnt(12)
	v_mfma_f32_32x32x16_bf16 v[32:47], v[156:159], v[132:135], v[32:47]
	v_max3_f32 v225, v225, v106, v107
	v_max3_f32 v224, v224, v105, v88
	v_max3_f32 v225, v225, v90, v91
	v_max3_f32 v224, v224, v89, v108
	ds_read_b64_tr_b16 v[132:133], v209 offset:33792
	ds_read_b64_tr_b16 v[134:135], v209 offset:34304
	v_mfma_f32_32x32x16_bf16 v[48:63], v[156:159], v[136:139], v[48:63]
	v_max3_f32 v225, v225, v110, v111
	v_max3_f32 v224, v224, v109, v92
	v_max3_f32 v225, v225, v94, v95
	v_max3_f32 v224, v224, v93, v225
	v_mov_b32_e32 v225, v224
	ds_read_b64_tr_b16 v[136:137], v209 offset:37888
	ds_read_b64_tr_b16 v[138:139], v209 offset:38400
	s_waitcnt lgkmcnt(12)
	v_mfma_f32_32x32x16_bf16 v[32:47], v[148:151], v[140:143], v[32:47]
	v_permlane32_swap_b32_e32 v224, v225
	v_max_f32_e32 v224, v224, v225
	v_cmp_lt_f32_e32 vcc, s33, v224
	v_add_f32_e32 v249, v215, v176
	s_mov_b64 s[20:21], vcc
	s_cbranch_vccnz .LBB0_321
